# v2 + SwiGLU epilogues of G1/G5 rewritten with packed f32 mul/add in 4-element groups (same f32 ops, bit-identical), no serial chains
# speedup vs baseline: 1.0014x; 1.0012x over previous
.LBB0_163:
	v_mov_b32_e32 v164, 0xbfb8aa3b
	s_lshl_b32 s5, s42, 7
	s_or_b32 s5, s5, s36
	s_mul_i32 s14, s41, 0x2c0000
	s_mul_hi_i32 s7, s41, 0x2c0000
	s_add_u32 s16, s34, s14
	s_addc_u32 s7, s35, s7
	s_ashr_i32 s14, s5, 6
	s_ashr_i32 s15, s14, 31
	s_lshl_b64 s[14:15], s[14:15], 15
	s_add_u32 s14, s16, s14
	s_addc_u32 s15, s7, s15
	v_lshl_add_u64 v[154:155], s[14:15], 0, v[2:3]
	v_lshl_add_u64 v[156:157], v[140:141], 1, v[154:155]
	s_mov_b64 s[14:15], -1
	s_movk_i32 s45, 0x3000
	s_mov_b32 s47, 0x11000
	s_mov_b32 s48, 0x9000
	v_pk_mul_f32 v[160:161], v[128:129], v[164:165] op_sel_hi:[1,0]
	v_pk_mul_f32 v[162:163], v[130:131], v[164:165] op_sel_hi:[1,0]
	v_exp_f32_e32 v160, v160
	v_exp_f32_e32 v161, v161
	v_exp_f32_e32 v162, v162
	v_exp_f32_e32 v163, v163
	v_pk_add_f32 v[160:161], v[160:161], 1.0 op_sel_hi:[1,0]
	v_pk_add_f32 v[162:163], v[162:163], 1.0 op_sel_hi:[1,0]
	v_rcp_f32_e32 v160, v160
	v_rcp_f32_e32 v161, v161
	v_rcp_f32_e32 v162, v162
	v_rcp_f32_e32 v163, v163
	v_pk_mul_f32 v[160:161], v[128:129], v[160:161]
	v_pk_mul_f32 v[162:163], v[130:131], v[162:163]
	v_pk_mul_f32 v[160:161], v[160:161], v[124:125]
	v_pk_mul_f32 v[162:163], v[162:163], v[126:127]
	v_cvt_pk_bf16_f32 v124, v160, v161
	v_cvt_pk_bf16_f32 v125, v162, v163
	v_pk_mul_f32 v[160:161], v[120:121], v[164:165] op_sel_hi:[1,0]
	v_pk_mul_f32 v[162:163], v[122:123], v[164:165] op_sel_hi:[1,0]
	v_exp_f32_e32 v160, v160
	v_exp_f32_e32 v161, v161
	v_exp_f32_e32 v162, v162
	v_exp_f32_e32 v163, v163
	v_pk_add_f32 v[160:161], v[160:161], 1.0 op_sel_hi:[1,0]
	v_pk_add_f32 v[162:163], v[162:163], 1.0 op_sel_hi:[1,0]
	v_rcp_f32_e32 v160, v160
	v_rcp_f32_e32 v161, v161
	v_rcp_f32_e32 v162, v162
	v_rcp_f32_e32 v163, v163
	v_pk_mul_f32 v[160:161], v[120:121], v[160:161]
	v_pk_mul_f32 v[162:163], v[122:123], v[162:163]
	v_pk_mul_f32 v[160:161], v[160:161], v[116:117]
	v_pk_mul_f32 v[162:163], v[162:163], v[118:119]
	v_cvt_pk_bf16_f32 v126, v160, v161
	v_cvt_pk_bf16_f32 v127, v162, v163
	global_store_dwordx4 v[156:157], v[124:127], off nt
	v_pk_mul_f32 v[160:161], v[112:113], v[164:165] op_sel_hi:[1,0]
	v_pk_mul_f32 v[162:163], v[114:115], v[164:165] op_sel_hi:[1,0]
	v_exp_f32_e32 v160, v160
	v_exp_f32_e32 v161, v161
	v_exp_f32_e32 v162, v162
	v_exp_f32_e32 v163, v163
	v_pk_add_f32 v[160:161], v[160:161], 1.0 op_sel_hi:[1,0]
	v_pk_add_f32 v[162:163], v[162:163], 1.0 op_sel_hi:[1,0]
	v_rcp_f32_e32 v160, v160
	v_rcp_f32_e32 v161, v161
	v_rcp_f32_e32 v162, v162
	v_rcp_f32_e32 v163, v163
	v_pk_mul_f32 v[160:161], v[112:113], v[160:161]
	v_pk_mul_f32 v[162:163], v[114:115], v[162:163]
	v_pk_mul_f32 v[160:161], v[160:161], v[108:109]
	v_pk_mul_f32 v[162:163], v[162:163], v[110:111]
	v_cvt_pk_bf16_f32 v108, v160, v161
	v_cvt_pk_bf16_f32 v109, v162, v163
	v_pk_mul_f32 v[160:161], v[104:105], v[164:165] op_sel_hi:[1,0]
	v_pk_mul_f32 v[162:163], v[106:107], v[164:165] op_sel_hi:[1,0]
	v_exp_f32_e32 v160, v160
	v_exp_f32_e32 v161, v161
	v_exp_f32_e32 v162, v162
	v_exp_f32_e32 v163, v163
	v_pk_add_f32 v[160:161], v[160:161], 1.0 op_sel_hi:[1,0]
	v_pk_add_f32 v[162:163], v[162:163], 1.0 op_sel_hi:[1,0]
	v_rcp_f32_e32 v160, v160
	v_rcp_f32_e32 v161, v161
	v_rcp_f32_e32 v162, v162
	v_rcp_f32_e32 v163, v163
	v_pk_mul_f32 v[160:161], v[104:105], v[160:161]
	v_pk_mul_f32 v[162:163], v[106:107], v[162:163]
	v_pk_mul_f32 v[160:161], v[160:161], v[100:101]
	v_pk_mul_f32 v[162:163], v[162:163], v[102:103]
	v_cvt_pk_bf16_f32 v110, v160, v161
	v_cvt_pk_bf16_f32 v111, v162, v163
	global_store_dwordx4 v[156:157], v[108:111], off offset:2048 nt
	v_pk_mul_f32 v[160:161], v[96:97], v[164:165] op_sel_hi:[1,0]
	v_pk_mul_f32 v[162:163], v[98:99], v[164:165] op_sel_hi:[1,0]
	v_exp_f32_e32 v160, v160
	v_exp_f32_e32 v161, v161
	v_exp_f32_e32 v162, v162
	v_exp_f32_e32 v163, v163
	v_pk_add_f32 v[160:161], v[160:161], 1.0 op_sel_hi:[1,0]
	v_pk_add_f32 v[162:163], v[162:163], 1.0 op_sel_hi:[1,0]
	v_rcp_f32_e32 v160, v160
	v_rcp_f32_e32 v161, v161
	v_rcp_f32_e32 v162, v162
	v_rcp_f32_e32 v163, v163
	v_pk_mul_f32 v[160:161], v[96:97], v[160:161]
	v_pk_mul_f32 v[162:163], v[98:99], v[162:163]
	v_pk_mul_f32 v[160:161], v[160:161], v[92:93]
	v_pk_mul_f32 v[162:163], v[162:163], v[94:95]
	v_cvt_pk_bf16_f32 v92, v160, v161
	v_cvt_pk_bf16_f32 v93, v162, v163
	v_pk_mul_f32 v[160:161], v[88:89], v[164:165] op_sel_hi:[1,0]
	v_pk_mul_f32 v[162:163], v[90:91], v[164:165] op_sel_hi:[1,0]
	v_exp_f32_e32 v160, v160
	v_exp_f32_e32 v161, v161
	v_exp_f32_e32 v162, v162
	v_exp_f32_e32 v163, v163
	v_pk_add_f32 v[160:161], v[160:161], 1.0 op_sel_hi:[1,0]
	v_pk_add_f32 v[162:163], v[162:163], 1.0 op_sel_hi:[1,0]
	v_rcp_f32_e32 v160, v160
	v_rcp_f32_e32 v161, v161
	v_rcp_f32_e32 v162, v162
	v_rcp_f32_e32 v163, v163
	v_pk_mul_f32 v[160:161], v[88:89], v[160:161]
	v_pk_mul_f32 v[162:163], v[90:91], v[162:163]
	v_pk_mul_f32 v[160:161], v[160:161], v[84:85]
	v_pk_mul_f32 v[162:163], v[162:163], v[86:87]
	v_cvt_pk_bf16_f32 v94, v160, v161
	v_cvt_pk_bf16_f32 v95, v162, v163
	v_add_co_u32_e32 v84, vcc, s51, v156
	s_nop 1
	v_addc_co_u32_e32 v85, vcc, 0, v157, vcc
	global_store_dwordx4 v[84:85], v[92:95], off nt
	s_andn2_b64 vcc, exec, s[8:9]
	v_pk_mul_f32 v[160:161], v[80:81], v[164:165] op_sel_hi:[1,0]
	v_pk_mul_f32 v[162:163], v[82:83], v[164:165] op_sel_hi:[1,0]
	v_exp_f32_e32 v160, v160
	v_exp_f32_e32 v161, v161
	v_exp_f32_e32 v162, v162
	v_exp_f32_e32 v163, v163
	v_pk_add_f32 v[160:161], v[160:161], 1.0 op_sel_hi:[1,0]
	v_pk_add_f32 v[162:163], v[162:163], 1.0 op_sel_hi:[1,0]
	v_rcp_f32_e32 v160, v160
	v_rcp_f32_e32 v161, v161
	v_rcp_f32_e32 v162, v162
	v_rcp_f32_e32 v163, v163
	v_pk_mul_f32 v[160:161], v[80:81], v[160:161]
	v_pk_mul_f32 v[162:163], v[82:83], v[162:163]
	v_pk_mul_f32 v[160:161], v[160:161], v[76:77]
	v_pk_mul_f32 v[162:163], v[162:163], v[78:79]
	v_cvt_pk_bf16_f32 v76, v160, v161
	v_cvt_pk_bf16_f32 v77, v162, v163
	v_pk_mul_f32 v[160:161], v[72:73], v[164:165] op_sel_hi:[1,0]
	v_pk_mul_f32 v[162:163], v[74:75], v[164:165] op_sel_hi:[1,0]
	v_exp_f32_e32 v160, v160
	v_exp_f32_e32 v161, v161
	v_exp_f32_e32 v162, v162
	v_exp_f32_e32 v163, v163
	v_pk_add_f32 v[160:161], v[160:161], 1.0 op_sel_hi:[1,0]
	v_pk_add_f32 v[162:163], v[162:163], 1.0 op_sel_hi:[1,0]
	v_rcp_f32_e32 v160, v160
	v_rcp_f32_e32 v161, v161
	v_rcp_f32_e32 v162, v162
	v_rcp_f32_e32 v163, v163
	v_pk_mul_f32 v[160:161], v[72:73], v[160:161]
	v_pk_mul_f32 v[162:163], v[74:75], v[162:163]
	v_pk_mul_f32 v[160:161], v[160:161], v[68:69]
	v_pk_mul_f32 v[162:163], v[162:163], v[70:71]
	v_cvt_pk_bf16_f32 v78, v160, v161
	v_cvt_pk_bf16_f32 v79, v162, v163
	global_store_dwordx4 v[84:85], v[76:79], off offset:2048 nt
	v_lshl_add_u64 v[68:69], v[142:143], 1, v[154:155]
	v_pk_mul_f32 v[160:161], v[64:65], v[164:165] op_sel_hi:[1,0]
	v_pk_mul_f32 v[162:163], v[66:67], v[164:165] op_sel_hi:[1,0]
	v_exp_f32_e32 v160, v160
	v_exp_f32_e32 v161, v161
	v_exp_f32_e32 v162, v162
	v_exp_f32_e32 v163, v163
	v_pk_add_f32 v[160:161], v[160:161], 1.0 op_sel_hi:[1,0]
	v_pk_add_f32 v[162:163], v[162:163], 1.0 op_sel_hi:[1,0]
	v_rcp_f32_e32 v160, v160
	v_rcp_f32_e32 v161, v161
	v_rcp_f32_e32 v162, v162
	v_rcp_f32_e32 v163, v163
	v_pk_mul_f32 v[160:161], v[64:65], v[160:161]
	v_pk_mul_f32 v[162:163], v[66:67], v[162:163]
	v_pk_mul_f32 v[160:161], v[160:161], v[60:61]
	v_pk_mul_f32 v[162:163], v[162:163], v[62:63]
	v_cvt_pk_bf16_f32 v60, v160, v161
	v_cvt_pk_bf16_f32 v61, v162, v163
	v_pk_mul_f32 v[160:161], v[56:57], v[164:165] op_sel_hi:[1,0]
	v_pk_mul_f32 v[162:163], v[58:59], v[164:165] op_sel_hi:[1,0]
	v_exp_f32_e32 v160, v160
	v_exp_f32_e32 v161, v161
	v_exp_f32_e32 v162, v162
	v_exp_f32_e32 v163, v163
	v_pk_add_f32 v[160:161], v[160:161], 1.0 op_sel_hi:[1,0]
	v_pk_add_f32 v[162:163], v[162:163], 1.0 op_sel_hi:[1,0]
	v_rcp_f32_e32 v160, v160
	v_rcp_f32_e32 v161, v161
	v_rcp_f32_e32 v162, v162
	v_rcp_f32_e32 v163, v163
	v_pk_mul_f32 v[160:161], v[56:57], v[160:161]
	v_pk_mul_f32 v[162:163], v[58:59], v[162:163]
	v_pk_mul_f32 v[160:161], v[160:161], v[52:53]
	v_pk_mul_f32 v[162:163], v[162:163], v[54:55]
	v_cvt_pk_bf16_f32 v62, v160, v161
	v_cvt_pk_bf16_f32 v63, v162, v163
	global_store_dwordx4 v[68:69], v[60:63], off nt
	v_lshl_add_u64 v[52:53], v[144:145], 1, v[154:155]
	v_pk_mul_f32 v[160:161], v[48:49], v[164:165] op_sel_hi:[1,0]
	v_pk_mul_f32 v[162:163], v[50:51], v[164:165] op_sel_hi:[1,0]
	v_exp_f32_e32 v160, v160
	v_exp_f32_e32 v161, v161
	v_exp_f32_e32 v162, v162
	v_exp_f32_e32 v163, v163
	v_pk_add_f32 v[160:161], v[160:161], 1.0 op_sel_hi:[1,0]
	v_pk_add_f32 v[162:163], v[162:163], 1.0 op_sel_hi:[1,0]
	v_rcp_f32_e32 v160, v160
	v_rcp_f32_e32 v161, v161
	v_rcp_f32_e32 v162, v162
	v_rcp_f32_e32 v163, v163
	v_pk_mul_f32 v[160:161], v[48:49], v[160:161]
	v_pk_mul_f32 v[162:163], v[50:51], v[162:163]
	v_pk_mul_f32 v[160:161], v[160:161], v[44:45]
	v_pk_mul_f32 v[162:163], v[162:163], v[46:47]
	v_cvt_pk_bf16_f32 v44, v160, v161
	v_cvt_pk_bf16_f32 v45, v162, v163
	v_pk_mul_f32 v[160:161], v[40:41], v[164:165] op_sel_hi:[1,0]
	v_pk_mul_f32 v[162:163], v[42:43], v[164:165] op_sel_hi:[1,0]
	v_exp_f32_e32 v160, v160
	v_exp_f32_e32 v161, v161
	v_exp_f32_e32 v162, v162
	v_exp_f32_e32 v163, v163
	v_pk_add_f32 v[160:161], v[160:161], 1.0 op_sel_hi:[1,0]
	v_pk_add_f32 v[162:163], v[162:163], 1.0 op_sel_hi:[1,0]
	v_rcp_f32_e32 v160, v160
	v_rcp_f32_e32 v161, v161
	v_rcp_f32_e32 v162, v162
	v_rcp_f32_e32 v163, v163
	v_pk_mul_f32 v[160:161], v[40:41], v[160:161]
	v_pk_mul_f32 v[162:163], v[42:43], v[162:163]
	v_pk_mul_f32 v[160:161], v[160:161], v[36:37]
	v_pk_mul_f32 v[162:163], v[162:163], v[38:39]
	v_cvt_pk_bf16_f32 v46, v160, v161
	v_cvt_pk_bf16_f32 v47, v162, v163
	global_store_dwordx4 v[52:53], v[44:47], off nt
	v_lshl_add_u64 v[36:37], v[146:147], 1, v[154:155]
	v_pk_mul_f32 v[160:161], v[32:33], v[164:165] op_sel_hi:[1,0]
	v_pk_mul_f32 v[162:163], v[34:35], v[164:165] op_sel_hi:[1,0]
	v_exp_f32_e32 v160, v160
	v_exp_f32_e32 v161, v161
	v_exp_f32_e32 v162, v162
	v_exp_f32_e32 v163, v163
	v_pk_add_f32 v[160:161], v[160:161], 1.0 op_sel_hi:[1,0]
	v_pk_add_f32 v[162:163], v[162:163], 1.0 op_sel_hi:[1,0]
	v_rcp_f32_e32 v160, v160
	v_rcp_f32_e32 v161, v161
	v_rcp_f32_e32 v162, v162
	v_rcp_f32_e32 v163, v163
	v_pk_mul_f32 v[160:161], v[32:33], v[160:161]
	v_pk_mul_f32 v[162:163], v[34:35], v[162:163]
	v_pk_mul_f32 v[160:161], v[160:161], v[28:29]
	v_pk_mul_f32 v[162:163], v[162:163], v[30:31]
	v_cvt_pk_bf16_f32 v28, v160, v161
	v_cvt_pk_bf16_f32 v29, v162, v163
	v_pk_mul_f32 v[160:161], v[24:25], v[164:165] op_sel_hi:[1,0]
	v_pk_mul_f32 v[162:163], v[26:27], v[164:165] op_sel_hi:[1,0]
	v_exp_f32_e32 v160, v160
	v_exp_f32_e32 v161, v161
	v_exp_f32_e32 v162, v162
	v_exp_f32_e32 v163, v163
	v_pk_add_f32 v[160:161], v[160:161], 1.0 op_sel_hi:[1,0]
	v_pk_add_f32 v[162:163], v[162:163], 1.0 op_sel_hi:[1,0]
	v_rcp_f32_e32 v160, v160
	v_rcp_f32_e32 v161, v161
	v_rcp_f32_e32 v162, v162
	v_rcp_f32_e32 v163, v163
	v_pk_mul_f32 v[160:161], v[24:25], v[160:161]
	v_pk_mul_f32 v[162:163], v[26:27], v[162:163]
	v_pk_mul_f32 v[160:161], v[160:161], v[20:21]
	v_pk_mul_f32 v[162:163], v[162:163], v[22:23]
	v_cvt_pk_bf16_f32 v30, v160, v161
	v_cvt_pk_bf16_f32 v31, v162, v163
	global_store_dwordx4 v[36:37], v[28:31], off nt
	v_lshl_add_u64 v[20:21], v[148:149], 1, v[154:155]
	v_pk_mul_f32 v[160:161], v[16:17], v[164:165] op_sel_hi:[1,0]
	v_pk_mul_f32 v[162:163], v[18:19], v[164:165] op_sel_hi:[1,0]
	v_exp_f32_e32 v160, v160
	v_exp_f32_e32 v161, v161
	v_exp_f32_e32 v162, v162
	v_exp_f32_e32 v163, v163
	v_pk_add_f32 v[160:161], v[160:161], 1.0 op_sel_hi:[1,0]
	v_pk_add_f32 v[162:163], v[162:163], 1.0 op_sel_hi:[1,0]
	v_rcp_f32_e32 v160, v160
	v_rcp_f32_e32 v161, v161
	v_rcp_f32_e32 v162, v162
	v_rcp_f32_e32 v163, v163
	v_pk_mul_f32 v[160:161], v[16:17], v[160:161]
	v_pk_mul_f32 v[162:163], v[18:19], v[162:163]
	v_pk_mul_f32 v[160:161], v[160:161], v[12:13]
	v_pk_mul_f32 v[162:163], v[162:163], v[14:15]
	v_cvt_pk_bf16_f32 v12, v160, v161
	v_cvt_pk_bf16_f32 v13, v162, v163
	v_pk_mul_f32 v[160:161], v[8:9], v[164:165] op_sel_hi:[1,0]
	v_pk_mul_f32 v[162:163], v[10:11], v[164:165] op_sel_hi:[1,0]
	v_exp_f32_e32 v160, v160
	v_exp_f32_e32 v161, v161
	v_exp_f32_e32 v162, v162
	v_exp_f32_e32 v163, v163
	v_pk_add_f32 v[160:161], v[160:161], 1.0 op_sel_hi:[1,0]
	v_pk_add_f32 v[162:163], v[162:163], 1.0 op_sel_hi:[1,0]
	v_rcp_f32_e32 v160, v160
	v_rcp_f32_e32 v161, v161
	v_rcp_f32_e32 v162, v162
	v_rcp_f32_e32 v163, v163
	v_pk_mul_f32 v[160:161], v[8:9], v[160:161]
	v_pk_mul_f32 v[162:163], v[10:11], v[162:163]
	v_pk_mul_f32 v[160:161], v[160:161], v[4:5]
	v_pk_mul_f32 v[162:163], v[162:163], v[6:7]
	v_cvt_pk_bf16_f32 v14, v160, v161
	v_cvt_pk_bf16_f32 v15, v162, v163
	global_store_dwordx4 v[20:21], v[12:15], off nt
	s_cbranch_vccnz .LBB0_156
	s_andn2_b64 vcc, exec, s[0:1]
	s_cbranch_vccnz .LBB0_155
	s_barrier
	s_branch .LBB0_155

.LBB0_747:
	v_mov_b32_e32 v164, 0xbfb8aa3b
	s_lshl_b32 s7, s44, 7
	s_or_b32 s7, s7, s38
	s_mul_i32 s16, s43, 0x2c0000
	s_mul_hi_i32 s11, s43, 0x2c0000
	s_add_u32 s18, s36, s16
	s_addc_u32 s11, s37, s11
	s_ashr_i32 s16, s7, 6
	s_ashr_i32 s17, s16, 31
	s_lshl_b64 s[16:17], s[16:17], 15
	s_add_u32 s16, s18, s16
	s_addc_u32 s17, s11, s17
	v_lshl_add_u64 v[154:155], s[16:17], 0, v[2:3]
	v_lshl_add_u64 v[156:157], v[140:141], 1, v[154:155]
	s_mov_b64 s[16:17], -1
	s_movk_i32 s45, 0x3000
	s_mov_b32 s47, 0x11000
	s_mov_b32 s48, 0x9000
	v_pk_mul_f32 v[160:161], v[128:129], v[164:165] op_sel_hi:[1,0]
	v_pk_mul_f32 v[162:163], v[130:131], v[164:165] op_sel_hi:[1,0]
	v_exp_f32_e32 v160, v160
	v_exp_f32_e32 v161, v161
	v_exp_f32_e32 v162, v162
	v_exp_f32_e32 v163, v163
	v_pk_add_f32 v[160:161], v[160:161], 1.0 op_sel_hi:[1,0]
	v_pk_add_f32 v[162:163], v[162:163], 1.0 op_sel_hi:[1,0]
	v_rcp_f32_e32 v160, v160
	v_rcp_f32_e32 v161, v161
	v_rcp_f32_e32 v162, v162
	v_rcp_f32_e32 v163, v163
	v_pk_mul_f32 v[160:161], v[128:129], v[160:161]
	v_pk_mul_f32 v[162:163], v[130:131], v[162:163]
	v_pk_mul_f32 v[160:161], v[160:161], v[124:125]
	v_pk_mul_f32 v[162:163], v[162:163], v[126:127]
	v_cvt_pk_bf16_f32 v124, v160, v161
	v_cvt_pk_bf16_f32 v125, v162, v163
	v_pk_mul_f32 v[160:161], v[120:121], v[164:165] op_sel_hi:[1,0]
	v_pk_mul_f32 v[162:163], v[122:123], v[164:165] op_sel_hi:[1,0]
	v_exp_f32_e32 v160, v160
	v_exp_f32_e32 v161, v161
	v_exp_f32_e32 v162, v162
	v_exp_f32_e32 v163, v163
	v_pk_add_f32 v[160:161], v[160:161], 1.0 op_sel_hi:[1,0]
	v_pk_add_f32 v[162:163], v[162:163], 1.0 op_sel_hi:[1,0]
	v_rcp_f32_e32 v160, v160
	v_rcp_f32_e32 v161, v161
	v_rcp_f32_e32 v162, v162
	v_rcp_f32_e32 v163, v163
	v_pk_mul_f32 v[160:161], v[120:121], v[160:161]
	v_pk_mul_f32 v[162:163], v[122:123], v[162:163]
	v_pk_mul_f32 v[160:161], v[160:161], v[116:117]
	v_pk_mul_f32 v[162:163], v[162:163], v[118:119]
	v_cvt_pk_bf16_f32 v126, v160, v161
	v_cvt_pk_bf16_f32 v127, v162, v163
	global_store_dwordx4 v[156:157], v[124:127], off nt
	v_pk_mul_f32 v[160:161], v[112:113], v[164:165] op_sel_hi:[1,0]
	v_pk_mul_f32 v[162:163], v[114:115], v[164:165] op_sel_hi:[1,0]
	v_exp_f32_e32 v160, v160
	v_exp_f32_e32 v161, v161
	v_exp_f32_e32 v162, v162
	v_exp_f32_e32 v163, v163
	v_pk_add_f32 v[160:161], v[160:161], 1.0 op_sel_hi:[1,0]
	v_pk_add_f32 v[162:163], v[162:163], 1.0 op_sel_hi:[1,0]
	v_rcp_f32_e32 v160, v160
	v_rcp_f32_e32 v161, v161
	v_rcp_f32_e32 v162, v162
	v_rcp_f32_e32 v163, v163
	v_pk_mul_f32 v[160:161], v[112:113], v[160:161]
	v_pk_mul_f32 v[162:163], v[114:115], v[162:163]
	v_pk_mul_f32 v[160:161], v[160:161], v[108:109]
	v_pk_mul_f32 v[162:163], v[162:163], v[110:111]
	v_cvt_pk_bf16_f32 v108, v160, v161
	v_cvt_pk_bf16_f32 v109, v162, v163
	v_pk_mul_f32 v[160:161], v[104:105], v[164:165] op_sel_hi:[1,0]
	v_pk_mul_f32 v[162:163], v[106:107], v[164:165] op_sel_hi:[1,0]
	v_exp_f32_e32 v160, v160
	v_exp_f32_e32 v161, v161
	v_exp_f32_e32 v162, v162
	v_exp_f32_e32 v163, v163
	v_pk_add_f32 v[160:161], v[160:161], 1.0 op_sel_hi:[1,0]
	v_pk_add_f32 v[162:163], v[162:163], 1.0 op_sel_hi:[1,0]
	v_rcp_f32_e32 v160, v160
	v_rcp_f32_e32 v161, v161
	v_rcp_f32_e32 v162, v162
	v_rcp_f32_e32 v163, v163
	v_pk_mul_f32 v[160:161], v[104:105], v[160:161]
	v_pk_mul_f32 v[162:163], v[106:107], v[162:163]
	v_pk_mul_f32 v[160:161], v[160:161], v[100:101]
	v_pk_mul_f32 v[162:163], v[162:163], v[102:103]
	v_cvt_pk_bf16_f32 v110, v160, v161
	v_cvt_pk_bf16_f32 v111, v162, v163
	global_store_dwordx4 v[156:157], v[108:111], off offset:2048 nt
	v_pk_mul_f32 v[160:161], v[96:97], v[164:165] op_sel_hi:[1,0]
	v_pk_mul_f32 v[162:163], v[98:99], v[164:165] op_sel_hi:[1,0]
	v_exp_f32_e32 v160, v160
	v_exp_f32_e32 v161, v161
	v_exp_f32_e32 v162, v162
	v_exp_f32_e32 v163, v163
	v_pk_add_f32 v[160:161], v[160:161], 1.0 op_sel_hi:[1,0]
	v_pk_add_f32 v[162:163], v[162:163], 1.0 op_sel_hi:[1,0]
	v_rcp_f32_e32 v160, v160
	v_rcp_f32_e32 v161, v161
	v_rcp_f32_e32 v162, v162
	v_rcp_f32_e32 v163, v163
	v_pk_mul_f32 v[160:161], v[96:97], v[160:161]
	v_pk_mul_f32 v[162:163], v[98:99], v[162:163]
	v_pk_mul_f32 v[160:161], v[160:161], v[92:93]
	v_pk_mul_f32 v[162:163], v[162:163], v[94:95]
	v_cvt_pk_bf16_f32 v92, v160, v161
	v_cvt_pk_bf16_f32 v93, v162, v163
	v_pk_mul_f32 v[160:161], v[88:89], v[164:165] op_sel_hi:[1,0]
	v_pk_mul_f32 v[162:163], v[90:91], v[164:165] op_sel_hi:[1,0]
	v_exp_f32_e32 v160, v160
	v_exp_f32_e32 v161, v161
	v_exp_f32_e32 v162, v162
	v_exp_f32_e32 v163, v163
	v_pk_add_f32 v[160:161], v[160:161], 1.0 op_sel_hi:[1,0]
	v_pk_add_f32 v[162:163], v[162:163], 1.0 op_sel_hi:[1,0]
	v_rcp_f32_e32 v160, v160
	v_rcp_f32_e32 v161, v161
	v_rcp_f32_e32 v162, v162
	v_rcp_f32_e32 v163, v163
	v_pk_mul_f32 v[160:161], v[88:89], v[160:161]
	v_pk_mul_f32 v[162:163], v[90:91], v[162:163]
	v_pk_mul_f32 v[160:161], v[160:161], v[84:85]
	v_pk_mul_f32 v[162:163], v[162:163], v[86:87]
	v_cvt_pk_bf16_f32 v94, v160, v161
	v_cvt_pk_bf16_f32 v95, v162, v163
	v_add_co_u32_e32 v84, vcc, s53, v156
	s_nop 1
	v_addc_co_u32_e32 v85, vcc, 0, v157, vcc
	global_store_dwordx4 v[84:85], v[92:95], off nt
	s_andn2_b64 vcc, exec, s[8:9]
	v_pk_mul_f32 v[160:161], v[80:81], v[164:165] op_sel_hi:[1,0]
	v_pk_mul_f32 v[162:163], v[82:83], v[164:165] op_sel_hi:[1,0]
	v_exp_f32_e32 v160, v160
	v_exp_f32_e32 v161, v161
	v_exp_f32_e32 v162, v162
	v_exp_f32_e32 v163, v163
	v_pk_add_f32 v[160:161], v[160:161], 1.0 op_sel_hi:[1,0]
	v_pk_add_f32 v[162:163], v[162:163], 1.0 op_sel_hi:[1,0]
	v_rcp_f32_e32 v160, v160
	v_rcp_f32_e32 v161, v161
	v_rcp_f32_e32 v162, v162
	v_rcp_f32_e32 v163, v163
	v_pk_mul_f32 v[160:161], v[80:81], v[160:161]
	v_pk_mul_f32 v[162:163], v[82:83], v[162:163]
	v_pk_mul_f32 v[160:161], v[160:161], v[76:77]
	v_pk_mul_f32 v[162:163], v[162:163], v[78:79]
	v_cvt_pk_bf16_f32 v76, v160, v161
	v_cvt_pk_bf16_f32 v77, v162, v163
	v_pk_mul_f32 v[160:161], v[72:73], v[164:165] op_sel_hi:[1,0]
	v_pk_mul_f32 v[162:163], v[74:75], v[164:165] op_sel_hi:[1,0]
	v_exp_f32_e32 v160, v160
	v_exp_f32_e32 v161, v161
	v_exp_f32_e32 v162, v162
	v_exp_f32_e32 v163, v163
	v_pk_add_f32 v[160:161], v[160:161], 1.0 op_sel_hi:[1,0]
	v_pk_add_f32 v[162:163], v[162:163], 1.0 op_sel_hi:[1,0]
	v_rcp_f32_e32 v160, v160
	v_rcp_f32_e32 v161, v161
	v_rcp_f32_e32 v162, v162
	v_rcp_f32_e32 v163, v163
	v_pk_mul_f32 v[160:161], v[72:73], v[160:161]
	v_pk_mul_f32 v[162:163], v[74:75], v[162:163]
	v_pk_mul_f32 v[160:161], v[160:161], v[68:69]
	v_pk_mul_f32 v[162:163], v[162:163], v[70:71]
	v_cvt_pk_bf16_f32 v78, v160, v161
	v_cvt_pk_bf16_f32 v79, v162, v163
	global_store_dwordx4 v[84:85], v[76:79], off offset:2048 nt
	v_lshl_add_u64 v[68:69], v[142:143], 1, v[154:155]
	v_pk_mul_f32 v[160:161], v[64:65], v[164:165] op_sel_hi:[1,0]
	v_pk_mul_f32 v[162:163], v[66:67], v[164:165] op_sel_hi:[1,0]
	v_exp_f32_e32 v160, v160
	v_exp_f32_e32 v161, v161
	v_exp_f32_e32 v162, v162
	v_exp_f32_e32 v163, v163
	v_pk_add_f32 v[160:161], v[160:161], 1.0 op_sel_hi:[1,0]
	v_pk_add_f32 v[162:163], v[162:163], 1.0 op_sel_hi:[1,0]
	v_rcp_f32_e32 v160, v160
	v_rcp_f32_e32 v161, v161
	v_rcp_f32_e32 v162, v162
	v_rcp_f32_e32 v163, v163
	v_pk_mul_f32 v[160:161], v[64:65], v[160:161]
	v_pk_mul_f32 v[162:163], v[66:67], v[162:163]
	v_pk_mul_f32 v[160:161], v[160:161], v[60:61]
	v_pk_mul_f32 v[162:163], v[162:163], v[62:63]
	v_cvt_pk_bf16_f32 v60, v160, v161
	v_cvt_pk_bf16_f32 v61, v162, v163
	v_pk_mul_f32 v[160:161], v[56:57], v[164:165] op_sel_hi:[1,0]
	v_pk_mul_f32 v[162:163], v[58:59], v[164:165] op_sel_hi:[1,0]
	v_exp_f32_e32 v160, v160
	v_exp_f32_e32 v161, v161
	v_exp_f32_e32 v162, v162
	v_exp_f32_e32 v163, v163
	v_pk_add_f32 v[160:161], v[160:161], 1.0 op_sel_hi:[1,0]
	v_pk_add_f32 v[162:163], v[162:163], 1.0 op_sel_hi:[1,0]
	v_rcp_f32_e32 v160, v160
	v_rcp_f32_e32 v161, v161
	v_rcp_f32_e32 v162, v162
	v_rcp_f32_e32 v163, v163
	v_pk_mul_f32 v[160:161], v[56:57], v[160:161]
	v_pk_mul_f32 v[162:163], v[58:59], v[162:163]
	v_pk_mul_f32 v[160:161], v[160:161], v[52:53]
	v_pk_mul_f32 v[162:163], v[162:163], v[54:55]
	v_cvt_pk_bf16_f32 v62, v160, v161
	v_cvt_pk_bf16_f32 v63, v162, v163
	global_store_dwordx4 v[68:69], v[60:63], off nt
	v_lshl_add_u64 v[52:53], v[144:145], 1, v[154:155]
	v_pk_mul_f32 v[160:161], v[48:49], v[164:165] op_sel_hi:[1,0]
	v_pk_mul_f32 v[162:163], v[50:51], v[164:165] op_sel_hi:[1,0]
	v_exp_f32_e32 v160, v160
	v_exp_f32_e32 v161, v161
	v_exp_f32_e32 v162, v162
	v_exp_f32_e32 v163, v163
	v_pk_add_f32 v[160:161], v[160:161], 1.0 op_sel_hi:[1,0]
	v_pk_add_f32 v[162:163], v[162:163], 1.0 op_sel_hi:[1,0]
	v_rcp_f32_e32 v160, v160
	v_rcp_f32_e32 v161, v161
	v_rcp_f32_e32 v162, v162
	v_rcp_f32_e32 v163, v163
	v_pk_mul_f32 v[160:161], v[48:49], v[160:161]
	v_pk_mul_f32 v[162:163], v[50:51], v[162:163]
	v_pk_mul_f32 v[160:161], v[160:161], v[44:45]
	v_pk_mul_f32 v[162:163], v[162:163], v[46:47]
	v_cvt_pk_bf16_f32 v44, v160, v161
	v_cvt_pk_bf16_f32 v45, v162, v163
	v_pk_mul_f32 v[160:161], v[40:41], v[164:165] op_sel_hi:[1,0]
	v_pk_mul_f32 v[162:163], v[42:43], v[164:165] op_sel_hi:[1,0]
	v_exp_f32_e32 v160, v160
	v_exp_f32_e32 v161, v161
	v_exp_f32_e32 v162, v162
	v_exp_f32_e32 v163, v163
	v_pk_add_f32 v[160:161], v[160:161], 1.0 op_sel_hi:[1,0]
	v_pk_add_f32 v[162:163], v[162:163], 1.0 op_sel_hi:[1,0]
	v_rcp_f32_e32 v160, v160
	v_rcp_f32_e32 v161, v161
	v_rcp_f32_e32 v162, v162
	v_rcp_f32_e32 v163, v163
	v_pk_mul_f32 v[160:161], v[40:41], v[160:161]
	v_pk_mul_f32 v[162:163], v[42:43], v[162:163]
	v_pk_mul_f32 v[160:161], v[160:161], v[36:37]
	v_pk_mul_f32 v[162:163], v[162:163], v[38:39]
	v_cvt_pk_bf16_f32 v46, v160, v161
	v_cvt_pk_bf16_f32 v47, v162, v163
	global_store_dwordx4 v[52:53], v[44:47], off nt
	v_lshl_add_u64 v[36:37], v[146:147], 1, v[154:155]
	v_pk_mul_f32 v[160:161], v[32:33], v[164:165] op_sel_hi:[1,0]
	v_pk_mul_f32 v[162:163], v[34:35], v[164:165] op_sel_hi:[1,0]
	v_exp_f32_e32 v160, v160
	v_exp_f32_e32 v161, v161
	v_exp_f32_e32 v162, v162
	v_exp_f32_e32 v163, v163
	v_pk_add_f32 v[160:161], v[160:161], 1.0 op_sel_hi:[1,0]
	v_pk_add_f32 v[162:163], v[162:163], 1.0 op_sel_hi:[1,0]
	v_rcp_f32_e32 v160, v160
	v_rcp_f32_e32 v161, v161
	v_rcp_f32_e32 v162, v162
	v_rcp_f32_e32 v163, v163
	v_pk_mul_f32 v[160:161], v[32:33], v[160:161]
	v_pk_mul_f32 v[162:163], v[34:35], v[162:163]
	v_pk_mul_f32 v[160:161], v[160:161], v[28:29]
	v_pk_mul_f32 v[162:163], v[162:163], v[30:31]
	v_cvt_pk_bf16_f32 v28, v160, v161
	v_cvt_pk_bf16_f32 v29, v162, v163
	v_pk_mul_f32 v[160:161], v[24:25], v[164:165] op_sel_hi:[1,0]
	v_pk_mul_f32 v[162:163], v[26:27], v[164:165] op_sel_hi:[1,0]
	v_exp_f32_e32 v160, v160
	v_exp_f32_e32 v161, v161
	v_exp_f32_e32 v162, v162
	v_exp_f32_e32 v163, v163
	v_pk_add_f32 v[160:161], v[160:161], 1.0 op_sel_hi:[1,0]
	v_pk_add_f32 v[162:163], v[162:163], 1.0 op_sel_hi:[1,0]
	v_rcp_f32_e32 v160, v160
	v_rcp_f32_e32 v161, v161
	v_rcp_f32_e32 v162, v162
	v_rcp_f32_e32 v163, v163
	v_pk_mul_f32 v[160:161], v[24:25], v[160:161]
	v_pk_mul_f32 v[162:163], v[26:27], v[162:163]
	v_pk_mul_f32 v[160:161], v[160:161], v[20:21]
	v_pk_mul_f32 v[162:163], v[162:163], v[22:23]
	v_cvt_pk_bf16_f32 v30, v160, v161
	v_cvt_pk_bf16_f32 v31, v162, v163
	global_store_dwordx4 v[36:37], v[28:31], off nt
	v_lshl_add_u64 v[20:21], v[148:149], 1, v[154:155]
	v_pk_mul_f32 v[160:161], v[16:17], v[164:165] op_sel_hi:[1,0]
	v_pk_mul_f32 v[162:163], v[18:19], v[164:165] op_sel_hi:[1,0]
	v_exp_f32_e32 v160, v160
	v_exp_f32_e32 v161, v161
	v_exp_f32_e32 v162, v162
	v_exp_f32_e32 v163, v163
	v_pk_add_f32 v[160:161], v[160:161], 1.0 op_sel_hi:[1,0]
	v_pk_add_f32 v[162:163], v[162:163], 1.0 op_sel_hi:[1,0]
	v_rcp_f32_e32 v160, v160
	v_rcp_f32_e32 v161, v161
	v_rcp_f32_e32 v162, v162
	v_rcp_f32_e32 v163, v163
	v_pk_mul_f32 v[160:161], v[16:17], v[160:161]
	v_pk_mul_f32 v[162:163], v[18:19], v[162:163]
	v_pk_mul_f32 v[160:161], v[160:161], v[12:13]
	v_pk_mul_f32 v[162:163], v[162:163], v[14:15]
	v_cvt_pk_bf16_f32 v12, v160, v161
	v_cvt_pk_bf16_f32 v13, v162, v163
	v_pk_mul_f32 v[160:161], v[8:9], v[164:165] op_sel_hi:[1,0]
	v_pk_mul_f32 v[162:163], v[10:11], v[164:165] op_sel_hi:[1,0]
	v_exp_f32_e32 v160, v160
	v_exp_f32_e32 v161, v161
	v_exp_f32_e32 v162, v162
	v_exp_f32_e32 v163, v163
	v_pk_add_f32 v[160:161], v[160:161], 1.0 op_sel_hi:[1,0]
	v_pk_add_f32 v[162:163], v[162:163], 1.0 op_sel_hi:[1,0]
	v_rcp_f32_e32 v160, v160
	v_rcp_f32_e32 v161, v161
	v_rcp_f32_e32 v162, v162
	v_rcp_f32_e32 v163, v163
	v_pk_mul_f32 v[160:161], v[8:9], v[160:161]
	v_pk_mul_f32 v[162:163], v[10:11], v[162:163]
	v_pk_mul_f32 v[160:161], v[160:161], v[4:5]
	v_pk_mul_f32 v[162:163], v[162:163], v[6:7]
	v_cvt_pk_bf16_f32 v14, v160, v161
	v_cvt_pk_bf16_f32 v15, v162, v163
	global_store_dwordx4 v[20:21], v[12:15], off nt
	s_cbranch_vccnz .LBB0_740
	s_andn2_b64 vcc, exec, s[0:1]
	s_cbranch_vccnz .LBB0_739
	s_barrier
	s_branch .LBB0_739
